# barrier-spin latency tuning: s_sleep 1 in the 42 grid-barrier poll loops replaced by s_nop 7 (tighter polling)
# baseline (speedup 1.0000x reference)
; __device__ __forceinline__ unsigned xb_ld(unsigned* p)              { return __hip_atomic_load(p, __ATOMIC_RELAXED, __HIP_MEMORY_SCOPE_AGENT); }
; __device__ __forceinline__ void xcd_barrier_complete(unsigned* bar, unsigned x, unsigned& nloc, unsigned& nx) {
;     ...
;     for (;;) {
;         sum = 0u; cnt = 0u; mine = 0u;
; #pragma unroll
;         for (unsigned j = 0; j < 16; ++j) { const unsigned c = xb_ld(&bar[XB_XCNT(j)]); sum += c; cnt += (c > 0u) ? 1u : 0u; mine = (j == x) ? c : mine; }
;         if (sum == G) break;
;         __builtin_amdgcn_s_sleep(1);
;         if ((++sp & 255u) == 0u) { if (xb_ld(&bar[XB_TMO])) break; if (sp > XB_SPIN_CAP) { atomicAdd(&bar[XB_TMO], 1u); break; } }
;     }
.Lb0_127:
	global_load_dword v15, v16, s[6:7] sc1
	global_load_dword v0, v16, s[8:9] sc1
	global_load_dword v1, v16, s[10:11] sc1
	global_load_dword v2, v16, s[12:13] sc1
	global_load_dword v3, v16, s[14:15] sc1
	global_load_dword v4, v16, s[16:17] sc1
	global_load_dword v5, v16, s[18:19] sc1
	global_load_dword v6, v16, s[20:21] sc1
	global_load_dword v7, v16, s[22:23] sc1
	global_load_dword v8, v16, s[24:25] sc1
	global_load_dword v9, v16, s[26:27] sc1
	global_load_dword v10, v16, s[28:29] sc1
	global_load_dword v11, v16, s[30:31] sc1
	global_load_dword v12, v16, s[34:35] sc1
	global_load_dword v13, v16, s[36:37] sc1
	global_load_dword v14, v16, s[38:39] sc1
	s_mov_b64 s[40:41], -1
	s_mov_b64 s[42:43], -1
	s_waitcnt vmcnt(14)
	v_add_u32_e32 v17, v0, v15
	s_waitcnt vmcnt(13)
	v_add_u32_e32 v17, v17, v1
	s_waitcnt vmcnt(12)
	v_add_u32_e32 v17, v17, v2
	s_waitcnt vmcnt(11)
	v_add_u32_e32 v17, v17, v3
	s_waitcnt vmcnt(10)
	v_add_u32_e32 v17, v17, v4
	s_waitcnt vmcnt(9)
	v_add_u32_e32 v17, v17, v5
	s_waitcnt vmcnt(8)
	v_add_u32_e32 v17, v17, v6
	s_waitcnt vmcnt(7)
	v_add_u32_e32 v17, v17, v7
	s_waitcnt vmcnt(6)
	v_add_u32_e32 v17, v17, v8
	s_waitcnt vmcnt(5)
	v_add_u32_e32 v17, v17, v9
	s_waitcnt vmcnt(4)
	v_add_u32_e32 v17, v17, v10
	s_waitcnt vmcnt(3)
	v_add_u32_e32 v17, v17, v11
	s_waitcnt vmcnt(2)
	v_add_u32_e32 v17, v17, v12
	s_waitcnt vmcnt(1)
	v_add_u32_e32 v17, v17, v13
	s_waitcnt vmcnt(0)
	v_add_u32_e32 v17, v17, v14
	v_cmp_eq_u32_e32 vcc, s33, v17
	s_cbranch_vccnz .Lb0_126
	s_and_b32 s40, s46, 0xff
	s_cmp_eq_u32 s40, 0
	s_mov_b64 s[40:41], -1
	s_mov_b64 s[44:45], -1
	s_nop 7
	s_cbranch_scc1 .Lb0_131
	s_and_b64 vcc, exec, s[44:45]
	s_cbranch_vccz .Lb0_126

.Lb0_145:
	s_and_b32 s20, s24, 0xff
	s_mov_b64 s[18:19], -1
	s_cmp_lg_u32 s20, 0
	s_mov_b64 s[22:23], -1
	s_nop 7
	s_cbranch_scc0 .Lb0_148
	s_and_b64 vcc, exec, s[22:23]
	s_cbranch_vccz .Lb0_144

.Lb0_162:
	s_and_b32 s18, s24, 0xff
	s_cmp_lg_u32 s18, 0
	s_mov_b64 s[20:21], -1
	s_nop 7
	s_cbranch_scc0 .Lb0_165
	s_mov_b64 s[22:23], -1
	s_and_b64 vcc, exec, s[20:21]
	s_cbranch_vccz .Lb0_161
